# v10 plus a 7us start stagger of odd pm-pair CU groups in P3 to de-synchronise the gate-load bursts
# baseline (speedup 1.0000x reference)
; __device__ __forceinline__ int lane_now() { int l; asm volatile("v_mbcnt_lo_u32_b32 %0, -1, 0\n\tv_mbcnt_hi_u32_b32 %0, -1, %0" : "=v"(l)); return l; }
; #define PG8_STAGE(bufoff, gbase, voff) do { _Pragma("unroll") for (int _i = 0; _i < 2; ++_i) \
;         __builtin_amdgcn_global_load_lds((const unsigned*)((const char*)(gbase) + (voff)[_i]), (PG8_LAS unsigned*)(lds + (bufoff) + ldsw + _i * 8192), 16, 0, 0); } while (0)
; template <class Epi, class Sched, bool ALIGN_EPI = false, bool SP2 = false>
; __device__ __forceinline__ void gemm_phase(PG8_LAS unsigned char* lds, const Gemm g, const Sched& S, const Epi& E, const int wave_s) {
;     int tid_ = (wave_s << 6) | lane_now(); asm volatile("" : "+v"(tid_));
;     const int tid = tid_, wid = __builtin_amdgcn_readfirstlane(tid >> 6), lane = tid & 63, wr = wid >> 2, wc = wid & 3, fr = lane & 15, fq = lane >> 4;
;     const int K = g.K, nt = K / BK, lda = g.lda, ldb = g.ldb;
;     unsigned voffA[2], voffB[2];
; #pragma unroll
;     for (int i = 0; i < 2; ++i) { int R, C; stage_rc(tid * 16 + i * 8192, R, C); const int Rb = Epi::PERM ? ((R & ~31) + perm32(R & 31)) : R;
;         voffA[i] = (unsigned)(R * lda + C) * 2u; voffB[i] = (unsigned)(Rb * ldb + C) * 2u; }
;     const size_t kstep = (size_t)(BK * 2);
;     const size_t hA = (size_t)HALF * lda * 2, hB = (size_t)HALF * ldb * 2;
;     const size_t tA = 2 * hA, tB = 2 * hB;
;     const unsigned ldsw = (unsigned)wid * 1024u;
;     const int aoff = lds_byte(wr * 64 + fr, fq * 8), boff = lds_byte(wc * 32 + fr, fq * 8);
;     ...
;     Unit cur, nxt; int ui = 0; float pf[8] = {0.f, 0.f, 0.f, 0.f, 0.f, 0.f, 0.f, 0.f};
;     if (!S.next(0, cur)) return;
;     f32x4 acc[2][2][4][2];
; #pragma unroll
;     for (int a = 0; a < 2; ++a)
; #pragma unroll
;         for (int b = 0; b < 2; ++b)
; #pragma unroll
;             for (int m = 0; m < 4; ++m)
; #pragma unroll
;                 for (int n = 0; n < 2; ++n) acc[a][b][m][n] = (f32x4){0.f, 0.f, 0.f, 0.f};
;     bf16x8 At[4][2], B0[2][2], B1[2][2];
;     const char* cA = (const char*)g.A + (size_t)cur.pm * tA; const char* cB = (const char*)g.Bt + (size_t)cur.pn * tB;
;     S.a_ready(cur);
;     if constexpr (SP2) {
;         PG8_STAGE(PG8_SB(0, 0), cB, voffB); PG8_STAGE(PG8_SB(0, 1), cB + hB, voffB); PG8_STAGE(PG8_SA(0, 0), cA, voffA); PG8_STAGE(PG8_SA(0, 1), cA + hA, voffA);
;         if (wr == 1) PG8_BAR;
.LBB0_613:
	s_waitcnt lgkmcnt(0)
	s_barrier
	s_bfe_u32 s3, s10, 0x10004
	s_cmp_eq_u32 s3, 0
	s_cbranch_scc1 .Lstag_P3_done
	s_lshl_b32 s3, s3, 1
.Lstag_P3_loop:
	s_sleep 127
	s_sub_u32 s3, s3, 1
	s_cmp_lg_u32 s3, 0
	s_cbranch_scc1 .Lstag_P3_loop
.Lstag_P3_done:
	v_mbcnt_lo_u32_b32 v0, -1, 0
	v_mbcnt_hi_u32_b32 v0, -1, v0
	s_cmpk_lt_i32 s10, 0x600
	v_or_b32_e32 v9, s84, v0
	s_cselect_b64 s[0:1], -1, 0
	s_cmpk_gt_i32 s10, 0x5ff
	v_readfirstlane_b32 s3, v9
	s_cbranch_scc1 .LBB0_631
	v_lshlrev_b32_e32 v0, 4, v9
	v_add_u32_e32 v1, 0x2000, v0
	v_ashrrev_i32_e32 v2, 31, v1
	v_lshrrev_b32_e32 v2, 22, v2
	v_add_u32_e32 v2, v1, v2
	v_ashrrev_i32_e32 v8, 10, v2
	v_mul_i32_i24_e32 v2, 0x400, v8
	v_sub_u32_e32 v1, v1, v2
	v_lshrrev_b32_e32 v2, 4, v1
	v_bitop3_b32 v1, v2, v1, 32 bitop3:0x6c
	v_ashrrev_i32_e32 v2, 31, v1
	v_lshrrev_b32_e32 v2, 26, v2
	v_add_u32_e32 v2, v1, v2
	v_lshlrev_b32_e32 v3, 3, v8
	v_ashrrev_i32_e32 v10, 6, v2
	v_and_b32_e32 v3, -16, v3
	v_add_u32_e32 v3, v10, v3
	v_and_b32_e32 v4, 3, v10
	s_mov_b32 s2, 0x1fffe0
	v_lshrrev_b32_e32 v5, 2, v3
	v_lshlrev_b32_e32 v6, 1, v3
	v_and_b32_e32 v2, 0xc0, v2
	v_and_or_b32 v4, v3, s2, v4
	v_and_b32_e32 v5, 4, v5
	v_and_b32_e32 v6, 24, v6
	v_sub_u32_e32 v1, v1, v2
	v_mov_b32_e32 v2, 1
	v_or3_b32 v4, v4, v5, v6
	v_lshlrev_b32_e32 v5, 5, v8
	v_ashrrev_i16_sdwa v1, v2, sext(v1) dst_sel:DWORD dst_unused:UNUSED_PAD src0_sel:DWORD src1_sel:BYTE_0
	v_and_b32_e32 v5, 32, v5
	v_bfe_i32 v11, v1, 0, 16
	v_add_lshl_u32 v1, v5, v11, 1
	v_lshl_add_u32 v132, v4, 11, v1
	v_lshl_add_u32 v134, v3, 11, v1
	v_bfe_i32 v1, v9, 27, 1
	v_lshrrev_b32_e32 v1, 22, v1
	v_add_u32_e32 v1, v0, v1
	v_and_b32_e32 v1, 0xfffffc00, v1
	v_sub_u32_e32 v0, v0, v1
	v_lshrrev_b32_e32 v1, 4, v0
	v_ashrrev_i32_e32 v3, 31, v9
	v_bitop3_b32 v0, v1, v0, 32 bitop3:0x6c
	v_lshrrev_b32_e32 v3, 26, v3
	v_ashrrev_i32_e32 v1, 31, v0
	v_add_u32_e32 v3, v9, v3
	v_lshrrev_b32_e32 v1, 26, v1
	v_ashrrev_i32_e32 v13, 6, v3
	v_add_u32_e32 v1, v0, v1
	v_lshlrev_b32_e32 v3, 3, v13
	v_ashrrev_i32_e32 v12, 6, v1
	v_and_b32_e32 v3, -16, v3
	v_add_u32_e32 v3, v12, v3
	v_and_b32_e32 v4, 3, v12
	s_ashr_i32 s73, s10, 31
	v_and_or_b32 v4, v3, s2, v4
	s_lshr_b32 s2, s73, 29
	s_add_i32 s2, s10, s2
	s_ashr_i32 s6, s3, 6
	s_ashr_i32 s4, s2, 3
	s_and_b32 s2, s2, -8
	s_ashr_i32 s7, s3, 8
	s_lshl_b32 s72, s6, 10
	s_sub_i32 s2, s10, s2
	s_cmp_lt_i32 s2, 0
	s_movk_i32 s74, 0xc1
	s_cselect_b32 s5, s74, 0xc0
	s_mul_i32 s2, s2, s5
	s_add_i32 s2, s2, s4
	s_ashr_i32 s4, s2, 31
	s_lshr_b32 s4, s4, 27
	s_add_i32 s4, s2, s4
	s_ashr_i32 s5, s4, 5
	s_andn2_b32 s4, s4, 31
	s_sub_i32 s4, s2, s4
	s_bfe_i32 s2, s4, 0x80000
	s_bfe_u32 s2, s2, 0x3000c
	s_add_i32 s8, s4, s2
	s_bfe_i32 s2, s8, 0x80000
	s_and_b32 s8, s8, 0xf8
	s_sub_i32 s4, s4, s8
	s_lshl_b32 s5, s5, 3
	s_sext_i32_i16 s2, s2
	s_sext_i32_i8 s4, s4
	v_lshrrev_b32_e32 v5, 2, v3
	v_lshlrev_b32_e32 v6, 1, v3
	v_and_b32_e32 v1, 0xc0, v1
	s_lshr_b32 s2, s2, 3
	s_add_i32 s66, s5, s4
	v_and_b32_e32 v5, 4, v5
	v_and_b32_e32 v6, 24, v6
	v_sub_u32_e32 v0, v0, v1
	s_ashr_i32 s67, s66, 31
	s_bfe_i64 s[8:9], s[2:3], 0x100000
	v_or3_b32 v4, v4, v5, v6
	v_lshlrev_b32_e32 v5, 5, v13
	v_ashrrev_i16_sdwa v0, v2, sext(v0) dst_sel:DWORD dst_unused:UNUSED_PAD src0_sel:DWORD src1_sel:BYTE_0
	s_lshl_b64 s[4:5], s[66:67], 19
	s_lshl_b64 s[8:9], s[8:9], 19
	v_and_b32_e32 v5, 32, v5
	v_bfe_i32 v14, v0, 0, 16
	s_add_u32 s68, s58, s8
	v_add_lshl_u32 v0, v5, v14, 1
	s_addc_u32 s69, s59, s9
	s_add_i32 s75, s72, 0
	v_lshl_add_u32 v136, v4, 11, v0
	s_add_i32 m0, s75, 0x10000
	v_lshl_add_u32 v138, v3, 11, v0
	global_load_lds_dwordx4 v136, s[68:69]
	s_add_i32 m0, s75, 0x12000
	s_add_u32 s8, s68, 0x40000
	global_load_lds_dwordx4 v132, s[68:69]
	s_addc_u32 s9, s69, 0
	s_add_i32 m0, s75, 0x14000
	v_mov_b32_e32 v137, 0
	global_load_lds_dwordx4 v136, s[8:9]
	s_add_i32 m0, s75, 0x16000
	s_add_u32 s64, s14, s4
	s_addc_u32 s65, s15, s5
	s_add_i32 s76, s75, 0x2000
	global_load_lds_dwordx4 v132, s[8:9]
	s_mov_b32 m0, s75
	s_add_u32 s4, s64, 0x40000
	global_load_lds_dwordx4 v138, s[64:65]
	s_mov_b32 m0, s76
	s_addc_u32 s5, s65, 0
	s_add_i32 s77, s75, 0x4000
	global_load_lds_dwordx4 v134, s[64:65]
	s_mov_b32 m0, s77
	s_add_i32 s78, s75, 0x6000
	global_load_lds_dwordx4 v138, s[4:5]
	s_mov_b32 m0, s78
	v_mov_b32_e32 v133, v137
	global_load_lds_dwordx4 v134, s[4:5]
	v_mov_b32_e32 v139, v137
	v_mov_b32_e32 v135, v137
	s_cmp_eq_u32 s7, 1
	s_mov_b32 s79, 0
	v_lshl_add_u64 v[6:7], s[68:69], 0, v[136:137]
	v_lshl_add_u64 v[4:5], s[68:69], 0, v[132:133]
	v_lshl_add_u64 v[0:1], s[64:65], 0, v[138:139]
	s_cselect_b64 s[4:5], -1, 0
	s_cmp_lg_u32 s7, 1
	v_lshl_add_u64 v[2:3], s[64:65], 0, v[134:135]
	s_cbranch_scc1 .LBB0_616
	s_barrier
